# LRU gate-matmul loop software-pipelined (fixed pending-load overwrite); mixer jobs re-paired ssd+lru / ret+gla
# baseline (speedup 1.0000x reference)
; #define LAS __attribute__((address_space(3)))
; __device__ __forceinline__ void lru_job(const bf16_t* P, bf16_t* Y, int l, int b, int kb, LAS float* lds, int wave_s) {
;     ...
;         for (int tt = 0; tt < 8; ++tt) { const int t = tg * 8 + tt; f32x2_t dd = {ba, bx};
; #pragma unroll
;             for (int i4 = 0; i4 < 16; ++i4) { const f32x4 xv = *(const LAS f32x4*)(XC + t * 64 + 4 * i4);
; #pragma unroll
;                 for (int q = 0; q < 4; ++q) { const f32x2_t xb = {xv[q], xv[q]}; dd = __builtin_elementwise_fma(xb, wax[4 * i4 + q], dd); } }
.LBB0_242:
	s_mov_b32 s10, 0
	ds_read_b128 v[216:219], v182
	ds_read_b128 v[220:223], v182 offset:16
	ds_read_b128 v[224:227], v182 offset:32
	ds_read_b128 v[228:231], v182 offset:48
	ds_read_b128 v[234:237], v182 offset:64
	ds_read_b128 v[238:241], v182 offset:80
	ds_read_b128 v[242:245], v182 offset:96
	ds_read_b128 v[246:249], v182 offset:112
	ds_read_b32 v134, v181

; #define LAS __attribute__((address_space(3)))
; __device__ __forceinline__ void lru_job(const bf16_t* P, bf16_t* Y, int l, int b, int kb, LAS float* lds, int wave_s) {
;     ...
;         for (int tt = 0; tt < 8; ++tt) { const int t = tg * 8 + tt; f32x2_t dd = {ba, bx};
; #pragma unroll
;             for (int i4 = 0; i4 < 16; ++i4) { const f32x4 xv = *(const LAS f32x4*)(XC + t * 64 + 4 * i4);
; #pragma unroll
;                 for (int q = 0; q < 4; ++q) { const f32x2_t xb = {xv[q], xv[q]}; dd = __builtin_elementwise_fma(xb, wax[4 * i4 + q], dd); } }
.LBB0_955:
	s_mov_b32 s10, 0
	ds_read_b128 v[216:219], v181
	ds_read_b128 v[220:223], v181 offset:16
	ds_read_b128 v[224:227], v181 offset:32
	ds_read_b128 v[228:231], v181 offset:48
	ds_read_b128 v[234:237], v181 offset:64
	ds_read_b128 v[238:241], v181 offset:80
	ds_read_b128 v[242:245], v181 offset:96
	ds_read_b128 v[246:249], v181 offset:112
	ds_read_b32 v134, v180
